# scan: loader/consumer LDS-DMA with per-image hand-off (3 barriers per chunk, ~1.5 chunks in flight)
# speedup vs baseline: 1.0142x; 1.0142x over previous
; #define PG8_LAS __attribute__((address_space(3)))
; __device__ __forceinline__ void phase_scan(const Args& a, PG8_LAS unsigned char* lds, int sblk) {
;     const int tid = threadIdx.x, lane = tid & 63, wave = tid >> 6, q = lane >> 4, r = lane & 15;
;     const int bh = sblk >> 1, dvh = sblk & 1, b = bh >> 2, h = bh & 3;
;     bf16_t* of = (bf16_t*)(a.ws + WS_OF2); const float* glast = (const float*)(a.ws + WS_GL);
;     constexpr int L_W = 0, L_QG = 17408, L_KD = 34816, L_UT = 53248, L_AQ = 71680;
;     f32x4 S[8];
; #pragma unroll
;     for (int m = 0; m < 8; ++m) S[m] = (f32x4){0.f, 0.f, 0.f, 0.f};
;     u32x4 pre[9];
;     { const unsigned char* src = a.ws + WS_PREP + (size_t)((b * 32 + 0) * 4 + h) * PREP_ITEM;
; #pragma unroll
;       for (int i = 0; i < 9; ++i) pre[i] = __builtin_nontemporal_load((const u32x4*)(src + (size_t)(tid + 512 * i) * 16)); }
.LBB0_523:
	s_andn2_b64 vcc, exec, s[0:1]
	s_cbranch_vccnz .LBB0_531
	v_readlane_b32 s0, v253, 17
	s_bitcmp0_b32 s0, 4
	s_mov_b32 s5, 0
	s_cbranch_scc1 .LBB0_531
	s_lshr_b32 s4, s82, 3
	s_bfe_u32 s8, s82, 0x20001
	s_and_b32 s30, s82, 1
	s_add_u32 s12, s16, 0x16000000
	s_addc_u32 s13, s17, 0
	s_lshl_b32 s0, s4, 7
	s_or_b32 s20, s0, s8
	s_mul_i32 s0, s20, 0x12000
	s_add_u32 s88, s12, s0
	s_addc_u32 s89, s13, 0
	v_mov_b32_e32 v95, 0
	s_waitcnt vmcnt(0)
	v_readfirstlane_b32 s56, v152
	s_mov_b32 s57, 0
	s_mov_b32 s86, 0
	s_lshr_b32 s56, s56, 6
	s_cmp_lt_u32 s56, 4
	s_cbranch_scc1 .Lsc_consumer
	s_cmp_lt_u32 s56, 6
	s_mov_b32 s69, 0x1c72
	s_cselect_b32 s69, 0xf10, s69
	s_cselect_b32 s70, 17, 9
	s_cselect_b32 s71, 15, 7
	s_movk_i32 s72, 0x80
	s_cselect_b32 s72, 0x100, s72
	s_mov_b32 s75, 0
	s_cmp_eq_u32 s56, 4
	s_cbranch_scc1 .Lsc_ld_w4
	s_cmp_eq_u32 s56, 5
	s_cbranch_scc1 .Lsc_ld_w5
	s_cmp_eq_u32 s56, 6
	s_cbranch_scc1 .Lsc_ld_w6
	s_mov_b32 s73, 0x10000
	s_lshl_b32 s74, s30, 13
	s_add_i32 s74, s74, 0xc000
	s_mov_b32 s75, 0xfffffdc0
	s_mov_b32 s60, 71680
	s_mov_b32 s62, 217344
	s_mul_i32 s61, s30, 0x2400
	s_add_i32 s61, s61, 44032
	s_xor_b32 s63, s61, 106496
	s_branch .Lsc_ld_tab
.Lsc_ld_w4:
	s_mov_b32 s73, 0x0
	s_mov_b32 s74, 0x0
	s_mov_b32 s60, 0
	s_mov_b32 s62, 80896
	s_mov_b32 s61, 0
	s_mov_b32 s63, 80896
	s_branch .Lsc_ld_tab

; #define PG8_LAS __attribute__((address_space(3)))
; __device__ __forceinline__ void phase_scan(const Args& a, PG8_LAS unsigned char* lds, int sblk) {
;     ...
;         for (int i = 0; i < 9; ++i) { const int p = tid + 512 * i; int off;
;             if (i < 2) off = L_W + (p >> 4) * 272 + (p & 15) * 16;
;             else if (i < 4) { const int pp = p - 1024; off = L_QG + (pp >> 4) * 272 + (pp & 15) * 16; }
;             else if (i < 6) { const int pp = p - 2048; off = L_KD + (pp >> 3) * 144 + (pp & 7) * 16; }
;             else if (i < 8) { const int pp = p - 3072; off = L_UT + (pp >> 3) * 144 + (pp & 7) * 16; }
;             else { const int pp = p - 4096; off = L_AQ + (pp >> 3) * 144 + (pp & 7) * 16; }
;             *(PG8_LAS u32x4*)(lds + off) = pre[i]; }
.Lsc_ld_tab:
	v_and_b32_e32 v165, 63, v152
	v_add_u32_e32 v156, 0, v165
	v_mul_u32_u24_e32 v157, s69, v156
	v_lshrrev_b32_e32 v157, 16, v157
	v_mul_u32_u24_e32 v158, s70, v157
	v_sub_u32_e32 v158, v156, v158
	v_min_u32_e32 v158, s71, v158
	v_lshlrev_b32_e32 v158, 4, v158
	v_mad_u32_u24 v170, v157, s72, v158
	v_add_u32_e32 v170, s73, v170
	v_add_u32_e32 v156, 64, v165
	v_mul_u32_u24_e32 v157, s69, v156
	v_lshrrev_b32_e32 v157, 16, v157
	v_mul_u32_u24_e32 v158, s70, v157
	v_sub_u32_e32 v158, v156, v158
	v_min_u32_e32 v158, s71, v158
	v_lshlrev_b32_e32 v158, 4, v158
	v_mad_u32_u24 v171, v157, s72, v158
	v_add_u32_e32 v171, s73, v171
	v_add_u32_e32 v156, 0x80, v165
	v_mul_u32_u24_e32 v157, s69, v156
	v_lshrrev_b32_e32 v157, 16, v157
	v_mul_u32_u24_e32 v158, s70, v157
	v_sub_u32_e32 v158, v156, v158
	v_min_u32_e32 v158, s71, v158
	v_lshlrev_b32_e32 v158, 4, v158
	v_mad_u32_u24 v172, v157, s72, v158
	v_add_u32_e32 v172, s73, v172
	v_add_u32_e32 v156, 0xc0, v165
	v_mul_u32_u24_e32 v157, s69, v156
	v_lshrrev_b32_e32 v157, 16, v157
	v_mul_u32_u24_e32 v158, s70, v157
	v_sub_u32_e32 v158, v156, v158
	v_min_u32_e32 v158, s71, v158
	v_lshlrev_b32_e32 v158, 4, v158
	v_mad_u32_u24 v173, v157, s72, v158
	v_add_u32_e32 v173, s73, v173
	v_add_u32_e32 v156, 0x100, v165
	v_mul_u32_u24_e32 v157, s69, v156
	v_lshrrev_b32_e32 v157, 16, v157
	v_mul_u32_u24_e32 v158, s70, v157
	v_sub_u32_e32 v158, v156, v158
	v_min_u32_e32 v158, s71, v158
	v_lshlrev_b32_e32 v158, 4, v158
	v_mad_u32_u24 v174, v157, s72, v158
	v_add_u32_e32 v174, s73, v174
	v_add_u32_e32 v156, 0x140, v165
	v_mul_u32_u24_e32 v157, s69, v156
	v_lshrrev_b32_e32 v157, 16, v157
	v_mul_u32_u24_e32 v158, s70, v157
	v_sub_u32_e32 v158, v156, v158
	v_min_u32_e32 v158, s71, v158
	v_lshlrev_b32_e32 v158, 4, v158
	v_mad_u32_u24 v175, v157, s72, v158
	v_add_u32_e32 v175, s73, v175
	v_add_u32_e32 v156, 0x180, v165
	v_mul_u32_u24_e32 v157, s69, v156
	v_lshrrev_b32_e32 v157, 16, v157
	v_mul_u32_u24_e32 v158, s70, v157
	v_sub_u32_e32 v158, v156, v158
	v_min_u32_e32 v158, s71, v158
	v_lshlrev_b32_e32 v158, 4, v158
	v_mad_u32_u24 v176, v157, s72, v158
	v_add_u32_e32 v176, s73, v176
	v_add_u32_e32 v156, 0x1c0, v165
	v_mul_u32_u24_e32 v157, s69, v156
	v_lshrrev_b32_e32 v157, 16, v157
	v_mul_u32_u24_e32 v158, s70, v157
	v_sub_u32_e32 v158, v156, v158
	v_min_u32_e32 v158, s71, v158
	v_lshlrev_b32_e32 v158, 4, v158
	v_mad_u32_u24 v177, v157, s72, v158
	v_add_u32_e32 v177, s73, v177
	v_add_u32_e32 v156, 0x200, v165
	v_mul_u32_u24_e32 v157, s69, v156
	v_lshrrev_b32_e32 v157, 16, v157
	v_mul_u32_u24_e32 v158, s70, v157
	v_sub_u32_e32 v158, v156, v158
	v_min_u32_e32 v158, s71, v158
	v_lshlrev_b32_e32 v158, 4, v158
	v_mad_u32_u24 v178, v157, s72, v158
	v_add_u32_e32 v178, s73, v178
	v_add_u32_e32 v156, 0x240, v165
	v_add_u32_e32 v156, s75, v156
	v_mul_u32_u24_e32 v157, s69, v156
	v_lshrrev_b32_e32 v157, 16, v157
	v_mul_u32_u24_e32 v158, s70, v157
	v_sub_u32_e32 v158, v156, v158
	v_min_u32_e32 v158, s71, v158
	v_lshlrev_b32_e32 v158, 4, v158
	v_mad_u32_u24 v179, v157, s72, v158
	v_add_u32_e32 v179, s74, v179
	v_add_u32_e32 v156, 0x280, v165
	v_add_u32_e32 v156, s75, v156
	v_mul_u32_u24_e32 v157, s69, v156
	v_lshrrev_b32_e32 v157, 16, v157
	v_mul_u32_u24_e32 v158, s70, v157
	v_sub_u32_e32 v158, v156, v158
	v_min_u32_e32 v158, s71, v158
	v_lshlrev_b32_e32 v158, 4, v158
	v_mad_u32_u24 v180, v157, s72, v158
	v_add_u32_e32 v180, s74, v180
	v_add_u32_e32 v156, 0x2c0, v165
	v_add_u32_e32 v156, s75, v156
	v_mul_u32_u24_e32 v157, s69, v156
	v_lshrrev_b32_e32 v157, 16, v157
	v_mul_u32_u24_e32 v158, s70, v157
	v_sub_u32_e32 v158, v156, v158
	v_min_u32_e32 v158, s71, v158
	v_lshlrev_b32_e32 v158, 4, v158
	v_mad_u32_u24 v181, v157, s72, v158
	v_add_u32_e32 v181, s74, v181
	v_add_u32_e32 v156, 0x300, v165
	v_add_u32_e32 v156, s75, v156
	v_mul_u32_u24_e32 v157, s69, v156
	v_lshrrev_b32_e32 v157, 16, v157
	v_mul_u32_u24_e32 v158, s70, v157
	v_sub_u32_e32 v158, v156, v158
	v_min_u32_e32 v158, s71, v158
	v_lshlrev_b32_e32 v158, 4, v158
	v_mad_u32_u24 v182, v157, s72, v158
	v_add_u32_e32 v182, s74, v182
	v_add_u32_e32 v156, 0x340, v165
	v_add_u32_e32 v156, s75, v156
	v_mul_u32_u24_e32 v157, s69, v156
	v_lshrrev_b32_e32 v157, 16, v157
	v_mul_u32_u24_e32 v158, s70, v157
	v_sub_u32_e32 v158, v156, v158
	v_min_u32_e32 v158, s71, v158
	v_lshlrev_b32_e32 v158, 4, v158
	v_mad_u32_u24 v183, v157, s72, v158
	v_add_u32_e32 v183, s74, v183
	v_add_u32_e32 v156, 0x380, v165
	v_add_u32_e32 v156, s75, v156
	v_mul_u32_u24_e32 v157, s69, v156
	v_lshrrev_b32_e32 v157, 16, v157
	v_mul_u32_u24_e32 v158, s70, v157
	v_sub_u32_e32 v158, v156, v158
	v_min_u32_e32 v158, s71, v158
	v_lshlrev_b32_e32 v158, 4, v158
	v_mad_u32_u24 v184, v157, s72, v158
	v_add_u32_e32 v184, s74, v184
	v_add_u32_e32 v156, 0x3c0, v165
	v_add_u32_e32 v156, s75, v156
	v_mul_u32_u24_e32 v157, s69, v156
	v_lshrrev_b32_e32 v157, 16, v157
	v_mul_u32_u24_e32 v158, s70, v157
	v_sub_u32_e32 v158, v156, v158
	v_min_u32_e32 v158, s71, v158
	v_lshlrev_b32_e32 v158, 4, v158
	v_mad_u32_u24 v185, v157, s72, v158
	v_add_u32_e32 v185, s74, v185
	v_add_u32_e32 v156, 0x400, v165
	v_add_u32_e32 v156, s75, v156
	v_mul_u32_u24_e32 v157, s69, v156
	v_lshrrev_b32_e32 v157, 16, v157
	v_mul_u32_u24_e32 v158, s70, v157
	v_sub_u32_e32 v158, v156, v158
	v_min_u32_e32 v158, s71, v158
	v_lshlrev_b32_e32 v158, 4, v158
	v_mad_u32_u24 v186, v157, s72, v158
	v_add_u32_e32 v186, s74, v186
	v_add_u32_e32 v156, 0x440, v165
	v_add_u32_e32 v156, s75, v156
	v_mul_u32_u24_e32 v157, s69, v156
	v_lshrrev_b32_e32 v157, 16, v157
	v_mul_u32_u24_e32 v158, s70, v157
	v_sub_u32_e32 v158, v156, v158
	v_min_u32_e32 v158, s71, v158
	v_lshlrev_b32_e32 v158, 4, v158
	v_mad_u32_u24 v187, v157, s72, v158
	v_add_u32_e32 v187, s74, v187
	s_cmp_eq_u32 s56, 4
	s_cbranch_scc1 .Lsc_l4
; #define PG8_LAS __attribute__((address_space(3)))
; __device__ __forceinline__ void phase_scan(const Args& a, PG8_LAS unsigned char* lds, int sblk) {
;     ...
;         for (int i = 0; i < 9; ++i) { const int p = tid + 512 * i; int off;
;             if (i < 2) off = L_W + (p >> 4) * 272 + (p & 15) * 16;
;             else if (i < 4) { const int pp = p - 1024; off = L_QG + (pp >> 4) * 272 + (pp & 15) * 16; }
;             else if (i < 6) { const int pp = p - 2048; off = L_KD + (pp >> 3) * 144 + (pp & 7) * 16; }
;             else if (i < 8) { const int pp = p - 3072; off = L_UT + (pp >> 3) * 144 + (pp & 7) * 16; }
;             else { const int pp = p - 4096; off = L_AQ + (pp >> 3) * 144 + (pp & 7) * 16; }
;             *(PG8_LAS u32x4*)(lds + off) = pre[i]; }
;         __syncthreads();
;         if (n + 1 < 32) { const unsigned char* src = a.ws + WS_PREP + (size_t)((b * 32 + n + 1) * 4 + h) * PREP_ITEM;
; #pragma unroll
;             for (int i = 0; i < 9; ++i) pre[i] = __builtin_nontemporal_load((const u32x4*)(src + (size_t)(tid + 512 * i) * 16)); }
	s_cmp_eq_u32 s56, 5
	s_cbranch_scc1 .Lsc_l5
	s_cmp_eq_u32 s56, 6
	s_cbranch_scc1 .Lsc_l6
	s_min_u32 s87, s86, 31
	s_mul_i32 s87, s87, 0x48000
	s_add_u32 s58, s88, s87
	s_addc_u32 s59, s89, 0
	s_add_i32 m0, s61, 0x2400
	s_nop 0
	global_load_lds_dwordx4 v179, s[58:59]
	s_add_i32 m0, s61, 0x2800
	s_nop 0
	global_load_lds_dwordx4 v180, s[58:59]
	s_add_i32 m0, s61, 0x2c00
	s_nop 0
	global_load_lds_dwordx4 v181, s[58:59]
	s_add_i32 m0, s61, 0x3000
	s_nop 0
	global_load_lds_dwordx4 v182, s[58:59]
	s_add_i32 m0, s61, 0x3400
	s_nop 0
	global_load_lds_dwordx4 v183, s[58:59]
	s_add_i32 m0, s61, 0x3800
	s_nop 0
	global_load_lds_dwordx4 v184, s[58:59]
	s_add_i32 m0, s61, 0x3c00
	s_nop 0
	global_load_lds_dwordx4 v185, s[58:59]
	s_add_i32 m0, s61, 0x4000
	s_nop 0
	global_load_lds_dwordx4 v186, s[58:59]
	s_add_i32 m0, s61, 0x4400
	s_nop 0
	global_load_lds_dwordx4 v187, s[58:59]
	s_mov_b32 m0, s60
	s_nop 0
	global_load_lds_dwordx4 v170, s[58:59]
	s_add_i32 m0, s60, 0x400
	s_nop 0
	global_load_lds_dwordx4 v171, s[58:59]
	s_add_i32 m0, s60, 0x800
	s_nop 0
	global_load_lds_dwordx4 v172, s[58:59]
	s_add_i32 m0, s60, 0xc00
	s_nop 0
	global_load_lds_dwordx4 v173, s[58:59]
	s_add_i32 m0, s60, 0x1000
	s_nop 0
	global_load_lds_dwordx4 v174, s[58:59]
	s_add_i32 m0, s60, 0x1400
	s_nop 0
	global_load_lds_dwordx4 v175, s[58:59]
	s_add_i32 m0, s60, 0x1800
	s_nop 0
	global_load_lds_dwordx4 v176, s[58:59]
	s_add_i32 m0, s60, 0x1c00
	s_nop 0
	global_load_lds_dwordx4 v177, s[58:59]
	s_add_i32 m0, s60, 0x2000
	s_nop 0
	global_load_lds_dwordx4 v178, s[58:59]
	s_xor_b32 s60, s60, s62
	s_xor_b32 s61, s61, s63
	s_add_i32 s86, s86, 1
	s_min_u32 s87, s86, 31
	s_mul_i32 s87, s87, 0x48000
	s_add_u32 s58, s88, s87
	s_addc_u32 s59, s89, 0
	s_add_i32 m0, s61, 0x2400
	s_nop 0
	global_load_lds_dwordx4 v179, s[58:59]
	s_add_i32 m0, s61, 0x2800
	s_nop 0
	global_load_lds_dwordx4 v180, s[58:59]
	s_add_i32 m0, s61, 0x2c00
	s_nop 0
	global_load_lds_dwordx4 v181, s[58:59]
	s_add_i32 m0, s61, 0x3000
	s_nop 0
	global_load_lds_dwordx4 v182, s[58:59]
	s_add_i32 m0, s61, 0x3400
	s_nop 0
	global_load_lds_dwordx4 v183, s[58:59]
	s_add_i32 m0, s61, 0x3800
	s_nop 0
	global_load_lds_dwordx4 v184, s[58:59]
	s_add_i32 m0, s61, 0x3c00
	s_nop 0
	global_load_lds_dwordx4 v185, s[58:59]
	s_add_i32 m0, s61, 0x4000
	s_nop 0
	global_load_lds_dwordx4 v186, s[58:59]
	s_add_i32 m0, s61, 0x4400
	s_nop 0
	global_load_lds_dwordx4 v187, s[58:59]
	s_mov_b32 m0, s60
	s_nop 0
	global_load_lds_dwordx4 v170, s[58:59]
	s_add_i32 m0, s60, 0x400
	s_nop 0
	global_load_lds_dwordx4 v171, s[58:59]
	s_add_i32 m0, s60, 0x800
	s_nop 0
	global_load_lds_dwordx4 v172, s[58:59]
	s_add_i32 m0, s60, 0xc00
	s_nop 0
	global_load_lds_dwordx4 v173, s[58:59]
	s_add_i32 m0, s60, 0x1000
	s_nop 0
	global_load_lds_dwordx4 v174, s[58:59]
	s_add_i32 m0, s60, 0x1400
	s_nop 0
	global_load_lds_dwordx4 v175, s[58:59]
	s_add_i32 m0, s60, 0x1800
	s_nop 0
	global_load_lds_dwordx4 v176, s[58:59]
	s_add_i32 m0, s60, 0x1c00
	s_nop 0
	global_load_lds_dwordx4 v177, s[58:59]
	s_add_i32 m0, s60, 0x2000
	s_nop 0
	global_load_lds_dwordx4 v178, s[58:59]
	s_xor_b32 s60, s60, s62
	s_xor_b32 s61, s61, s63
	s_add_i32 s86, s86, 1
	s_waitcnt vmcnt(27)
	s_barrier
.Lsc_l7_loop:
	s_waitcnt vmcnt(18)
	s_barrier
	s_min_u32 s87, s86, 31
	s_mul_i32 s87, s87, 0x48000
	s_add_u32 s58, s88, s87
	s_addc_u32 s59, s89, 0
	s_add_i32 m0, s61, 0x2400
	s_nop 0
	global_load_lds_dwordx4 v179, s[58:59]
	s_add_i32 m0, s61, 0x2800
	s_nop 0
	global_load_lds_dwordx4 v180, s[58:59]
	s_add_i32 m0, s61, 0x2c00
	s_nop 0
	global_load_lds_dwordx4 v181, s[58:59]
	s_add_i32 m0, s61, 0x3000
	s_nop 0
	global_load_lds_dwordx4 v182, s[58:59]
	s_add_i32 m0, s61, 0x3400
	s_nop 0
	global_load_lds_dwordx4 v183, s[58:59]
	s_add_i32 m0, s61, 0x3800
	s_nop 0
	global_load_lds_dwordx4 v184, s[58:59]
	s_add_i32 m0, s61, 0x3c00
	s_nop 0
	global_load_lds_dwordx4 v185, s[58:59]
	s_add_i32 m0, s61, 0x4000
	s_nop 0
	global_load_lds_dwordx4 v186, s[58:59]
	s_add_i32 m0, s61, 0x4400
	s_nop 0
	global_load_lds_dwordx4 v187, s[58:59]
	s_barrier
	s_mov_b32 m0, s60
	s_nop 0
	global_load_lds_dwordx4 v170, s[58:59]
	s_add_i32 m0, s60, 0x400
	s_nop 0
	global_load_lds_dwordx4 v171, s[58:59]
	s_add_i32 m0, s60, 0x800
	s_nop 0
	global_load_lds_dwordx4 v172, s[58:59]
	s_add_i32 m0, s60, 0xc00
	s_nop 0
	global_load_lds_dwordx4 v173, s[58:59]
	s_add_i32 m0, s60, 0x1000
	s_nop 0
	global_load_lds_dwordx4 v174, s[58:59]
	s_add_i32 m0, s60, 0x1400
	s_nop 0
	global_load_lds_dwordx4 v175, s[58:59]
	s_add_i32 m0, s60, 0x1800
	s_nop 0
	global_load_lds_dwordx4 v176, s[58:59]
	s_add_i32 m0, s60, 0x1c00
	s_nop 0
	global_load_lds_dwordx4 v177, s[58:59]
	s_add_i32 m0, s60, 0x2000
	s_nop 0
	global_load_lds_dwordx4 v178, s[58:59]
	s_xor_b32 s60, s60, s62
	s_xor_b32 s61, s61, s63
	s_add_i32 s86, s86, 1
	s_waitcnt vmcnt(27)
	s_barrier
	s_add_i32 s57, s57, 1
	s_cmp_lt_u32 s57, 32
	s_cbranch_scc1 .Lsc_l7_loop
	s_waitcnt vmcnt(0)
	s_branch .LBB0_531
; #define PG8_LAS __attribute__((address_space(3)))
; __device__ __forceinline__ void phase_scan(const Args& a, PG8_LAS unsigned char* lds, int sblk) {
;     ...
;         for (int i = 0; i < 9; ++i) { const int p = tid + 512 * i; int off;
;             if (i < 2) off = L_W + (p >> 4) * 272 + (p & 15) * 16;
;             else if (i < 4) { const int pp = p - 1024; off = L_QG + (pp >> 4) * 272 + (pp & 15) * 16; }
;             else if (i < 6) { const int pp = p - 2048; off = L_KD + (pp >> 3) * 144 + (pp & 7) * 16; }
;             else if (i < 8) { const int pp = p - 3072; off = L_UT + (pp >> 3) * 144 + (pp & 7) * 16; }
;             else { const int pp = p - 4096; off = L_AQ + (pp >> 3) * 144 + (pp & 7) * 16; }
;             *(PG8_LAS u32x4*)(lds + off) = pre[i]; }
;         __syncthreads();
;         if (n + 1 < 32) { const unsigned char* src = a.ws + WS_PREP + (size_t)((b * 32 + n + 1) * 4 + h) * PREP_ITEM;
; #pragma unroll
;             for (int i = 0; i < 9; ++i) pre[i] = __builtin_nontemporal_load((const u32x4*)(src + (size_t)(tid + 512 * i) * 16)); }
.Lsc_l4:
	s_min_u32 s87, s86, 31
	s_mul_i32 s87, s87, 0x48000
	s_add_u32 s58, s88, s87
	s_addc_u32 s59, s89, 0
	s_mov_b32 m0, s60
	s_nop 0
	global_load_lds_dwordx4 v170, s[58:59]
	s_add_i32 m0, s60, 0x400
	s_nop 0
	global_load_lds_dwordx4 v171, s[58:59]
	s_add_i32 m0, s60, 0x800
	s_nop 0
	global_load_lds_dwordx4 v172, s[58:59]
	s_add_i32 m0, s60, 0xc00
	s_nop 0
	global_load_lds_dwordx4 v173, s[58:59]
	s_add_i32 m0, s60, 0x1000
	s_nop 0
	global_load_lds_dwordx4 v174, s[58:59]
	s_add_i32 m0, s60, 0x1400
	s_nop 0
	global_load_lds_dwordx4 v175, s[58:59]
	s_add_i32 m0, s60, 0x1800
	s_nop 0
	global_load_lds_dwordx4 v176, s[58:59]
	s_add_i32 m0, s60, 0x1c00
	s_nop 0
	global_load_lds_dwordx4 v177, s[58:59]
	s_add_i32 m0, s60, 0x2000
	s_nop 0
	global_load_lds_dwordx4 v178, s[58:59]
	s_add_i32 m0, s61, 0x2400
	s_nop 0
	global_load_lds_dwordx4 v179, s[58:59]
	s_add_i32 m0, s61, 0x2800
	s_nop 0
	global_load_lds_dwordx4 v180, s[58:59]
	s_add_i32 m0, s61, 0x2c00
	s_nop 0
	global_load_lds_dwordx4 v181, s[58:59]
	s_add_i32 m0, s61, 0x3000
	s_nop 0
	global_load_lds_dwordx4 v182, s[58:59]
	s_add_i32 m0, s61, 0x3400
	s_nop 0
	global_load_lds_dwordx4 v183, s[58:59]
	s_add_i32 m0, s61, 0x3800
	s_nop 0
	global_load_lds_dwordx4 v184, s[58:59]
	s_add_i32 m0, s61, 0x3c00
	s_nop 0
	global_load_lds_dwordx4 v185, s[58:59]
	s_add_i32 m0, s61, 0x4000
	s_nop 0
	global_load_lds_dwordx4 v186, s[58:59]
	s_xor_b32 s60, s60, s62
	s_xor_b32 s61, s61, s63
	s_add_i32 s86, s86, 1
	s_min_u32 s87, s86, 31
	s_mul_i32 s87, s87, 0x48000
	s_add_u32 s58, s88, s87
	s_addc_u32 s59, s89, 0
	s_mov_b32 m0, s60
	s_nop 0
	global_load_lds_dwordx4 v170, s[58:59]
	s_add_i32 m0, s60, 0x400
	s_nop 0
	global_load_lds_dwordx4 v171, s[58:59]
	s_add_i32 m0, s60, 0x800
	s_nop 0
	global_load_lds_dwordx4 v172, s[58:59]
	s_add_i32 m0, s60, 0xc00
	s_nop 0
	global_load_lds_dwordx4 v173, s[58:59]
	s_add_i32 m0, s60, 0x1000
	s_nop 0
	global_load_lds_dwordx4 v174, s[58:59]
	s_add_i32 m0, s60, 0x1400
	s_nop 0
	global_load_lds_dwordx4 v175, s[58:59]
	s_add_i32 m0, s60, 0x1800
	s_nop 0
	global_load_lds_dwordx4 v176, s[58:59]
	s_add_i32 m0, s60, 0x1c00
	s_nop 0
	global_load_lds_dwordx4 v177, s[58:59]
	s_add_i32 m0, s60, 0x2000
	s_nop 0
	global_load_lds_dwordx4 v178, s[58:59]
	s_add_i32 m0, s61, 0x2400
	s_nop 0
	global_load_lds_dwordx4 v179, s[58:59]
	s_add_i32 m0, s61, 0x2800
	s_nop 0
	global_load_lds_dwordx4 v180, s[58:59]
	s_add_i32 m0, s61, 0x2c00
	s_nop 0
	global_load_lds_dwordx4 v181, s[58:59]
	s_add_i32 m0, s61, 0x3000
	s_nop 0
	global_load_lds_dwordx4 v182, s[58:59]
	s_add_i32 m0, s61, 0x3400
	s_nop 0
	global_load_lds_dwordx4 v183, s[58:59]
	s_add_i32 m0, s61, 0x3800
	s_nop 0
	global_load_lds_dwordx4 v184, s[58:59]
	s_add_i32 m0, s61, 0x3c00
	s_nop 0
	global_load_lds_dwordx4 v185, s[58:59]
	s_add_i32 m0, s61, 0x4000
	s_nop 0
	global_load_lds_dwordx4 v186, s[58:59]
	s_xor_b32 s60, s60, s62
	s_xor_b32 s61, s61, s63
	s_add_i32 s86, s86, 1
	s_waitcnt vmcnt(17)
	s_barrier
.Lsc_l4_loop:
	s_barrier
	s_min_u32 s87, s86, 31
	s_mul_i32 s87, s87, 0x48000
	s_add_u32 s58, s88, s87
	s_addc_u32 s59, s89, 0
	s_mov_b32 m0, s60
	s_nop 0
	global_load_lds_dwordx4 v170, s[58:59]
	s_add_i32 m0, s60, 0x400
	s_nop 0
	global_load_lds_dwordx4 v171, s[58:59]
	s_add_i32 m0, s60, 0x800
	s_nop 0
	global_load_lds_dwordx4 v172, s[58:59]
	s_add_i32 m0, s60, 0xc00
	s_nop 0
	global_load_lds_dwordx4 v173, s[58:59]
	s_add_i32 m0, s60, 0x1000
	s_nop 0
	global_load_lds_dwordx4 v174, s[58:59]
	s_add_i32 m0, s60, 0x1400
	s_nop 0
	global_load_lds_dwordx4 v175, s[58:59]
	s_add_i32 m0, s60, 0x1800
	s_nop 0
	global_load_lds_dwordx4 v176, s[58:59]
	s_add_i32 m0, s60, 0x1c00
	s_nop 0
	global_load_lds_dwordx4 v177, s[58:59]
	s_add_i32 m0, s60, 0x2000
	s_nop 0
	global_load_lds_dwordx4 v178, s[58:59]
	s_add_i32 m0, s61, 0x2400
	s_nop 0
	global_load_lds_dwordx4 v179, s[58:59]
	s_add_i32 m0, s61, 0x2800
	s_nop 0
	global_load_lds_dwordx4 v180, s[58:59]
	s_add_i32 m0, s61, 0x2c00
	s_nop 0
	global_load_lds_dwordx4 v181, s[58:59]
	s_add_i32 m0, s61, 0x3000
	s_nop 0
	global_load_lds_dwordx4 v182, s[58:59]
	s_add_i32 m0, s61, 0x3400
	s_nop 0
	global_load_lds_dwordx4 v183, s[58:59]
	s_add_i32 m0, s61, 0x3800
	s_nop 0
	global_load_lds_dwordx4 v184, s[58:59]
	s_add_i32 m0, s61, 0x3c00
	s_nop 0
	global_load_lds_dwordx4 v185, s[58:59]
	s_add_i32 m0, s61, 0x4000
	s_nop 0
	global_load_lds_dwordx4 v186, s[58:59]
	s_xor_b32 s60, s60, s62
	s_xor_b32 s61, s61, s63
	s_add_i32 s86, s86, 1
	s_barrier
	s_waitcnt vmcnt(17)
	s_barrier
	s_add_i32 s57, s57, 1
	s_cmp_lt_u32 s57, 32
	s_cbranch_scc1 .Lsc_l4_loop
	s_waitcnt vmcnt(0)
	s_branch .LBB0_531
; #define PG8_LAS __attribute__((address_space(3)))
; __device__ __forceinline__ void phase_scan(const Args& a, PG8_LAS unsigned char* lds, int sblk) {
;     ...
;         for (int i = 0; i < 9; ++i) { const int p = tid + 512 * i; int off;
;             if (i < 2) off = L_W + (p >> 4) * 272 + (p & 15) * 16;
;             else if (i < 4) { const int pp = p - 1024; off = L_QG + (pp >> 4) * 272 + (pp & 15) * 16; }
;             else if (i < 6) { const int pp = p - 2048; off = L_KD + (pp >> 3) * 144 + (pp & 7) * 16; }
;             else if (i < 8) { const int pp = p - 3072; off = L_UT + (pp >> 3) * 144 + (pp & 7) * 16; }
;             else { const int pp = p - 4096; off = L_AQ + (pp >> 3) * 144 + (pp & 7) * 16; }
;             *(PG8_LAS u32x4*)(lds + off) = pre[i]; }
;         __syncthreads();
;         if (n + 1 < 32) { const unsigned char* src = a.ws + WS_PREP + (size_t)((b * 32 + n + 1) * 4 + h) * PREP_ITEM;
; #pragma unroll
;             for (int i = 0; i < 9; ++i) pre[i] = __builtin_nontemporal_load((const u32x4*)(src + (size_t)(tid + 512 * i) * 16)); }
.Lsc_l5:
	s_min_u32 s87, s86, 31
	s_mul_i32 s87, s87, 0x48000
	s_add_u32 s58, s88, s87
	s_addc_u32 s59, s89, 0
	s_mov_b32 m0, s60
	s_nop 0
	global_load_lds_dwordx4 v170, s[58:59]
	s_add_i32 m0, s60, 0x400
	s_nop 0
	global_load_lds_dwordx4 v171, s[58:59]
	s_add_i32 m0, s60, 0x800
	s_nop 0
	global_load_lds_dwordx4 v172, s[58:59]
	s_add_i32 m0, s60, 0xc00
	s_nop 0
	global_load_lds_dwordx4 v173, s[58:59]
	s_add_i32 m0, s60, 0x1000
	s_nop 0
	global_load_lds_dwordx4 v174, s[58:59]
	s_add_i32 m0, s60, 0x1400
	s_nop 0
	global_load_lds_dwordx4 v175, s[58:59]
	s_add_i32 m0, s60, 0x1800
	s_nop 0
	global_load_lds_dwordx4 v176, s[58:59]
	s_add_i32 m0, s60, 0x1c00
	s_nop 0
	global_load_lds_dwordx4 v177, s[58:59]
	s_add_i32 m0, s60, 0x2000
	s_nop 0
	global_load_lds_dwordx4 v178, s[58:59]
	s_add_i32 m0, s61, 0x2400
	s_nop 0
	global_load_lds_dwordx4 v179, s[58:59]
	s_add_i32 m0, s61, 0x2800
	s_nop 0
	global_load_lds_dwordx4 v180, s[58:59]
	s_add_i32 m0, s61, 0x2c00
	s_nop 0
	global_load_lds_dwordx4 v181, s[58:59]
	s_add_i32 m0, s61, 0x3000
	s_nop 0
	global_load_lds_dwordx4 v182, s[58:59]
	s_add_i32 m0, s61, 0x3400
	s_nop 0
	global_load_lds_dwordx4 v183, s[58:59]
	s_add_i32 m0, s61, 0x3800
	s_nop 0
	global_load_lds_dwordx4 v184, s[58:59]
	s_add_i32 m0, s61, 0x3c00
	s_nop 0
	global_load_lds_dwordx4 v185, s[58:59]
	s_add_i32 m0, s61, 0x4000
	s_nop 0
	global_load_lds_dwordx4 v186, s[58:59]
	s_xor_b32 s60, s60, s62
	s_xor_b32 s61, s61, s63
	s_add_i32 s86, s86, 1
	s_min_u32 s87, s86, 31
	s_mul_i32 s87, s87, 0x48000
	s_add_u32 s58, s88, s87
	s_addc_u32 s59, s89, 0
	s_mov_b32 m0, s60
	s_nop 0
	global_load_lds_dwordx4 v170, s[58:59]
	s_add_i32 m0, s60, 0x400
	s_nop 0
	global_load_lds_dwordx4 v171, s[58:59]
	s_add_i32 m0, s60, 0x800
	s_nop 0
	global_load_lds_dwordx4 v172, s[58:59]
	s_add_i32 m0, s60, 0xc00
	s_nop 0
	global_load_lds_dwordx4 v173, s[58:59]
	s_add_i32 m0, s60, 0x1000
	s_nop 0
	global_load_lds_dwordx4 v174, s[58:59]
	s_add_i32 m0, s60, 0x1400
	s_nop 0
	global_load_lds_dwordx4 v175, s[58:59]
	s_add_i32 m0, s60, 0x1800
	s_nop 0
	global_load_lds_dwordx4 v176, s[58:59]
	s_add_i32 m0, s60, 0x1c00
	s_nop 0
	global_load_lds_dwordx4 v177, s[58:59]
	s_add_i32 m0, s60, 0x2000
	s_nop 0
	global_load_lds_dwordx4 v178, s[58:59]
	s_add_i32 m0, s61, 0x2400
	s_nop 0
	global_load_lds_dwordx4 v179, s[58:59]
	s_add_i32 m0, s61, 0x2800
	s_nop 0
	global_load_lds_dwordx4 v180, s[58:59]
	s_add_i32 m0, s61, 0x2c00
	s_nop 0
	global_load_lds_dwordx4 v181, s[58:59]
	s_add_i32 m0, s61, 0x3000
	s_nop 0
	global_load_lds_dwordx4 v182, s[58:59]
	s_add_i32 m0, s61, 0x3400
	s_nop 0
	global_load_lds_dwordx4 v183, s[58:59]
	s_add_i32 m0, s61, 0x3800
	s_nop 0
	global_load_lds_dwordx4 v184, s[58:59]
	s_add_i32 m0, s61, 0x3c00
	s_nop 0
	global_load_lds_dwordx4 v185, s[58:59]
	s_add_i32 m0, s61, 0x4000
	s_nop 0
	global_load_lds_dwordx4 v186, s[58:59]
	s_xor_b32 s60, s60, s62
	s_xor_b32 s61, s61, s63
	s_add_i32 s86, s86, 1
	s_barrier
.Lsc_l5_loop:
	s_waitcnt vmcnt(17)
	s_barrier
	s_barrier
	s_min_u32 s87, s86, 31
	s_mul_i32 s87, s87, 0x48000
	s_add_u32 s58, s88, s87
	s_addc_u32 s59, s89, 0
	s_mov_b32 m0, s60
	s_nop 0
	global_load_lds_dwordx4 v170, s[58:59]
	s_add_i32 m0, s60, 0x400
	s_nop 0
	global_load_lds_dwordx4 v171, s[58:59]
	s_add_i32 m0, s60, 0x800
	s_nop 0
	global_load_lds_dwordx4 v172, s[58:59]
	s_add_i32 m0, s60, 0xc00
	s_nop 0
	global_load_lds_dwordx4 v173, s[58:59]
	s_add_i32 m0, s60, 0x1000
	s_nop 0
	global_load_lds_dwordx4 v174, s[58:59]
	s_add_i32 m0, s60, 0x1400
	s_nop 0
	global_load_lds_dwordx4 v175, s[58:59]
	s_add_i32 m0, s60, 0x1800
	s_nop 0
	global_load_lds_dwordx4 v176, s[58:59]
	s_add_i32 m0, s60, 0x1c00
	s_nop 0
	global_load_lds_dwordx4 v177, s[58:59]
	s_add_i32 m0, s60, 0x2000
	s_nop 0
	global_load_lds_dwordx4 v178, s[58:59]
	s_add_i32 m0, s61, 0x2400
	s_nop 0
	global_load_lds_dwordx4 v179, s[58:59]
	s_add_i32 m0, s61, 0x2800
	s_nop 0
	global_load_lds_dwordx4 v180, s[58:59]
	s_add_i32 m0, s61, 0x2c00
	s_nop 0
	global_load_lds_dwordx4 v181, s[58:59]
	s_add_i32 m0, s61, 0x3000
	s_nop 0
	global_load_lds_dwordx4 v182, s[58:59]
	s_add_i32 m0, s61, 0x3400
	s_nop 0
	global_load_lds_dwordx4 v183, s[58:59]
	s_add_i32 m0, s61, 0x3800
	s_nop 0
	global_load_lds_dwordx4 v184, s[58:59]
	s_add_i32 m0, s61, 0x3c00
	s_nop 0
	global_load_lds_dwordx4 v185, s[58:59]
	s_add_i32 m0, s61, 0x4000
	s_nop 0
	global_load_lds_dwordx4 v186, s[58:59]
	s_xor_b32 s60, s60, s62
	s_xor_b32 s61, s61, s63
	s_add_i32 s86, s86, 1
	s_barrier
	s_add_i32 s57, s57, 1
	s_cmp_lt_u32 s57, 32
	s_cbranch_scc1 .Lsc_l5_loop
	s_waitcnt vmcnt(0)
	s_branch .LBB0_531
; #define PG8_LAS __attribute__((address_space(3)))
; __device__ __forceinline__ void phase_scan(const Args& a, PG8_LAS unsigned char* lds, int sblk) {
;     ...
;         for (int i = 0; i < 9; ++i) { const int p = tid + 512 * i; int off;
;             if (i < 2) off = L_W + (p >> 4) * 272 + (p & 15) * 16;
;             else if (i < 4) { const int pp = p - 1024; off = L_QG + (pp >> 4) * 272 + (pp & 15) * 16; }
;             else if (i < 6) { const int pp = p - 2048; off = L_KD + (pp >> 3) * 144 + (pp & 7) * 16; }
;             else if (i < 8) { const int pp = p - 3072; off = L_UT + (pp >> 3) * 144 + (pp & 7) * 16; }
;             else { const int pp = p - 4096; off = L_AQ + (pp >> 3) * 144 + (pp & 7) * 16; }
;             *(PG8_LAS u32x4*)(lds + off) = pre[i]; }
;         __syncthreads();
;         if (n + 1 < 32) { const unsigned char* src = a.ws + WS_PREP + (size_t)((b * 32 + n + 1) * 4 + h) * PREP_ITEM;
; #pragma unroll
;             for (int i = 0; i < 9; ++i) pre[i] = __builtin_nontemporal_load((const u32x4*)(src + (size_t)(tid + 512 * i) * 16)); }
.Lsc_l6:
	s_min_u32 s87, s86, 31
	s_mul_i32 s87, s87, 0x48000
	s_add_u32 s58, s88, s87
	s_addc_u32 s59, s89, 0
	s_mov_b32 m0, s60
	s_nop 0
	global_load_lds_dwordx4 v170, s[58:59]
	s_add_i32 m0, s60, 0x400
	s_nop 0
	global_load_lds_dwordx4 v171, s[58:59]
	s_add_i32 m0, s60, 0x800
	s_nop 0
	global_load_lds_dwordx4 v172, s[58:59]
	s_add_i32 m0, s60, 0xc00
	s_nop 0
	global_load_lds_dwordx4 v173, s[58:59]
	s_add_i32 m0, s60, 0x1000
	s_nop 0
	global_load_lds_dwordx4 v174, s[58:59]
	s_add_i32 m0, s60, 0x1400
	s_nop 0
	global_load_lds_dwordx4 v175, s[58:59]
	s_add_i32 m0, s60, 0x1800
	s_nop 0
	global_load_lds_dwordx4 v176, s[58:59]
	s_add_i32 m0, s60, 0x1c00
	s_nop 0
	global_load_lds_dwordx4 v177, s[58:59]
	s_add_i32 m0, s60, 0x2000
	s_nop 0
	global_load_lds_dwordx4 v178, s[58:59]
	s_add_i32 m0, s61, 0x2400
	s_nop 0
	global_load_lds_dwordx4 v179, s[58:59]
	s_add_i32 m0, s61, 0x2800
	s_nop 0
	global_load_lds_dwordx4 v180, s[58:59]
	s_add_i32 m0, s61, 0x2c00
	s_nop 0
	global_load_lds_dwordx4 v181, s[58:59]
	s_add_i32 m0, s61, 0x3000
	s_nop 0
	global_load_lds_dwordx4 v182, s[58:59]
	s_add_i32 m0, s61, 0x3400
	s_nop 0
	global_load_lds_dwordx4 v183, s[58:59]
	s_add_i32 m0, s61, 0x3800
	s_nop 0
	global_load_lds_dwordx4 v184, s[58:59]
	s_add_i32 m0, s61, 0x3c00
	s_nop 0
	global_load_lds_dwordx4 v185, s[58:59]
	s_add_i32 m0, s61, 0x4000
	s_nop 0
	global_load_lds_dwordx4 v186, s[58:59]
	s_add_i32 m0, s61, 0x4400
	s_nop 0
	global_load_lds_dwordx4 v187, s[58:59]
	s_xor_b32 s60, s60, s62
	s_xor_b32 s61, s61, s63
	s_add_i32 s86, s86, 1
	s_min_u32 s87, s86, 31
	s_mul_i32 s87, s87, 0x48000
	s_add_u32 s58, s88, s87
	s_addc_u32 s59, s89, 0
	s_mov_b32 m0, s60
	s_nop 0
	global_load_lds_dwordx4 v170, s[58:59]
	s_add_i32 m0, s60, 0x400
	s_nop 0
	global_load_lds_dwordx4 v171, s[58:59]
	s_add_i32 m0, s60, 0x800
	s_nop 0
	global_load_lds_dwordx4 v172, s[58:59]
	s_add_i32 m0, s60, 0xc00
	s_nop 0
	global_load_lds_dwordx4 v173, s[58:59]
	s_add_i32 m0, s60, 0x1000
	s_nop 0
	global_load_lds_dwordx4 v174, s[58:59]
	s_add_i32 m0, s60, 0x1400
	s_nop 0
	global_load_lds_dwordx4 v175, s[58:59]
	s_add_i32 m0, s60, 0x1800
	s_nop 0
	global_load_lds_dwordx4 v176, s[58:59]
	s_add_i32 m0, s60, 0x1c00
	s_nop 0
	global_load_lds_dwordx4 v177, s[58:59]
	s_add_i32 m0, s60, 0x2000
	s_nop 0
	global_load_lds_dwordx4 v178, s[58:59]
	s_add_i32 m0, s61, 0x2400
	s_nop 0
	global_load_lds_dwordx4 v179, s[58:59]
	s_add_i32 m0, s61, 0x2800
	s_nop 0
	global_load_lds_dwordx4 v180, s[58:59]
	s_add_i32 m0, s61, 0x2c00
	s_nop 0
	global_load_lds_dwordx4 v181, s[58:59]
	s_add_i32 m0, s61, 0x3000
	s_nop 0
	global_load_lds_dwordx4 v182, s[58:59]
	s_add_i32 m0, s61, 0x3400
	s_nop 0
	global_load_lds_dwordx4 v183, s[58:59]
	s_add_i32 m0, s61, 0x3800
	s_nop 0
	global_load_lds_dwordx4 v184, s[58:59]
	s_add_i32 m0, s61, 0x3c00
	s_nop 0
	global_load_lds_dwordx4 v185, s[58:59]
	s_add_i32 m0, s61, 0x4000
	s_nop 0
	global_load_lds_dwordx4 v186, s[58:59]
	s_add_i32 m0, s61, 0x4400
	s_nop 0
	global_load_lds_dwordx4 v187, s[58:59]
	s_xor_b32 s60, s60, s62
	s_xor_b32 s61, s61, s63
	s_add_i32 s86, s86, 1
	s_barrier
.Lsc_l6_loop:
	s_barrier
	s_waitcnt vmcnt(18)
	s_barrier
	s_barrier
	s_min_u32 s87, s86, 31
	s_mul_i32 s87, s87, 0x48000
	s_add_u32 s58, s88, s87
	s_addc_u32 s59, s89, 0
	s_mov_b32 m0, s60
	s_nop 0
	global_load_lds_dwordx4 v170, s[58:59]
	s_add_i32 m0, s60, 0x400
	s_nop 0
	global_load_lds_dwordx4 v171, s[58:59]
	s_add_i32 m0, s60, 0x800
	s_nop 0
	global_load_lds_dwordx4 v172, s[58:59]
	s_add_i32 m0, s60, 0xc00
	s_nop 0
	global_load_lds_dwordx4 v173, s[58:59]
	s_add_i32 m0, s60, 0x1000
	s_nop 0
	global_load_lds_dwordx4 v174, s[58:59]
	s_add_i32 m0, s60, 0x1400
	s_nop 0
	global_load_lds_dwordx4 v175, s[58:59]
	s_add_i32 m0, s60, 0x1800
	s_nop 0
	global_load_lds_dwordx4 v176, s[58:59]
	s_add_i32 m0, s60, 0x1c00
	s_nop 0
	global_load_lds_dwordx4 v177, s[58:59]
	s_add_i32 m0, s60, 0x2000
	s_nop 0
	global_load_lds_dwordx4 v178, s[58:59]
	s_add_i32 m0, s61, 0x2400
	s_nop 0
	global_load_lds_dwordx4 v179, s[58:59]
	s_add_i32 m0, s61, 0x2800
	s_nop 0
	global_load_lds_dwordx4 v180, s[58:59]
	s_add_i32 m0, s61, 0x2c00
	s_nop 0
	global_load_lds_dwordx4 v181, s[58:59]
	s_add_i32 m0, s61, 0x3000
	s_nop 0
	global_load_lds_dwordx4 v182, s[58:59]
	s_add_i32 m0, s61, 0x3400
	s_nop 0
	global_load_lds_dwordx4 v183, s[58:59]
	s_add_i32 m0, s61, 0x3800
	s_nop 0
	global_load_lds_dwordx4 v184, s[58:59]
	s_add_i32 m0, s61, 0x3c00
	s_nop 0
	global_load_lds_dwordx4 v185, s[58:59]
	s_add_i32 m0, s61, 0x4000
	s_nop 0
	global_load_lds_dwordx4 v186, s[58:59]
	s_add_i32 m0, s61, 0x4400
	s_nop 0
	global_load_lds_dwordx4 v187, s[58:59]
	s_xor_b32 s60, s60, s62
	s_xor_b32 s61, s61, s63
	s_add_i32 s86, s86, 1
	s_add_i32 s57, s57, 1
	s_cmp_lt_u32 s57, 32
	s_cbranch_scc1 .Lsc_l6_loop
	s_waitcnt vmcnt(0)
	s_branch .LBB0_531

; #define PG8_LAS __attribute__((address_space(3)))
; __device__ __forceinline__ float bf_lo(unsigned w) { return __uint_as_float(w << 16); }
; __device__ __forceinline__ float bf_hi(unsigned w) { return __uint_as_float(w & 0xffff0000u); }
; #define MFMA16(a, b, c) __builtin_amdgcn_mfma_f32_16x16x32_bf16((a), (b), (c), 0, 0, 0)
; __device__ __forceinline__ bf16x8 packf8(const f32x4 lo, const f32x4 hi) { u32x4 p; p.x = pk2(lo[0], lo[1]); p.y = pk2(lo[2], lo[3]); p.z = pk2(hi[0], hi[1]); p.w = pk2(hi[2], hi[3]); return __builtin_bit_cast(bf16x8, p); }
; __device__ __forceinline__ void phase_scan(const Args& a, PG8_LAS unsigned char* lds, int sblk) {
;     ...
;         if (wave < 4) {
;             __builtin_amdgcn_s_setprio(2);
;             const int dv0 = dvh * 64 + wave * 16; const float gl = glast[(b * 32 + n) * 4 + h]; const size_t row0 = (size_t)b * 2048 + n * 64;
;             bf16x8 Sb[4];
; #pragma unroll
;             for (int s = 0; s < 4; ++s) Sb[s] = packf8(S[2 * s], S[2 * s + 1]);
;             f32x4 vn[4];
; #pragma unroll
;             for (int mt = 0; mt < 4; ++mt) {
;                 const u32x2 uu = *(const PG8_LAS u32x2*)(lds + L_UT + (dv0 + r) * 144 + (16 * mt + 4 * q) * 2);
;                 f32x4 acc = {0.f, 0.f, 0.f, 0.f};
; #pragma unroll
;                 for (int s = 0; s < 4; ++s) { const bf16x8 af = *(const PG8_LAS bf16x8*)(lds + L_W + (16 * mt + r) * 272 + (32 * s + 8 * q) * 2); acc = MFMA16(af, Sb[s], acc); }
;                 vn[mt] = (f32x4){bf_lo(uu.x), bf_hi(uu.x), bf_lo(uu.y), bf_hi(uu.y)} - acc;
;             }
;             bf16x8 Vb[2];
; #pragma unroll
;             for (int s = 0; s < 2; ++s) Vb[s] = packf8(vn[2 * s], vn[2 * s + 1]);
.Lsc_cs_loop:
	v_readlane_b32 s54, v154, s57
	v_add_u32_e32 v160, s64, v120
	v_add_u32_e32 v161, s66, v121
	s_setprio 2
	v_mov_b32_e32 v106, s54
	v_cvt_pk_bf16_f32 v76, v48, v49
	v_cvt_pk_bf16_f32 v77, v50, v51
	v_cvt_pk_bf16_f32 v78, v44, v45
	v_cvt_pk_bf16_f32 v79, v46, v47
	v_cvt_pk_bf16_f32 v80, v40, v41
	v_cvt_pk_bf16_f32 v81, v42, v43
	v_cvt_pk_bf16_f32 v82, v36, v37
	v_cvt_pk_bf16_f32 v83, v38, v39
	v_cvt_pk_bf16_f32 v84, v56, v57
	v_cvt_pk_bf16_f32 v85, v58, v59
	v_cvt_pk_bf16_f32 v86, v60, v61
	v_cvt_pk_bf16_f32 v87, v62, v63
	v_cvt_pk_bf16_f32 v88, v64, v65
	v_cvt_pk_bf16_f32 v89, v66, v67
	v_cvt_pk_bf16_f32 v90, v52, v53
	v_cvt_pk_bf16_f32 v91, v54, v55
	ds_read_b128 v[68:71], v160
	ds_read_b128 v[72:75], v160 offset:64
	s_waitcnt lgkmcnt(1)
	v_mfma_f32_16x16x32_bf16 v[68:71], v[68:71], v[76:79], 0
	ds_read_b128 v[122:125], v160 offset:128
	ds_read_b128 v[130:133], v160 offset:4480
	ds_read_b128 v[134:137], v160 offset:4544
	s_waitcnt lgkmcnt(3)
	v_mfma_f32_16x16x32_bf16 v[68:71], v[72:75], v[80:83], v[68:71]
	ds_read_b128 v[72:75], v160 offset:192
	v_add_u32_e32 v108, s67, v119
	ds_read2_b64 v[126:129], v108 offset1:4
	s_waitcnt lgkmcnt(4)
	v_mfma_f32_16x16x32_bf16 v[68:71], v[122:125], v[84:87], v[68:71]
	ds_read_b128 v[122:125], v160 offset:4352
	s_waitcnt lgkmcnt(1)
	v_lshlrev_b32_e32 v138, 16, v127
	v_and_b32_e32 v127, 0xffff0000, v127
	v_mfma_f32_16x16x32_bf16 v[68:71], v[72:75], v[88:91], v[68:71]
	ds_read_b128 v[72:75], v160 offset:4416
	v_lshlrev_b32_e32 v109, 16, v126
	v_and_b32_e32 v126, 0xffff0000, v126
	s_waitcnt lgkmcnt(1)
	v_mfma_f32_16x16x32_bf16 v[122:125], v[122:125], v[76:79], 0
	v_pk_mul_f32 v[50:51], v[50:51], v[106:107] op_sel_hi:[1,0]
	s_waitcnt lgkmcnt(0)
	v_mfma_f32_16x16x32_bf16 v[72:75], v[72:75], v[80:83], v[122:125]
	v_sub_f32_e32 v142, v138, v70
	v_sub_f32_e32 v143, v127, v71
	ds_read_b128 v[138:141], v160 offset:8896
	s_nop 0
	ds_read_b128 v[122:125], v160 offset:8704
	v_mfma_f32_16x16x32_bf16 v[72:75], v[130:133], v[84:87], v[72:75]
	ds_read_b128 v[130:133], v160 offset:8768
	v_sub_f32_e32 v109, v109, v68
	v_sub_f32_e32 v144, v126, v69
	v_mfma_f32_16x16x32_bf16 v[70:73], v[134:137], v[88:91], v[72:75]
	ds_read_b128 v[134:137], v160 offset:8832
	v_lshlrev_b32_e32 v68, 16, v128
	v_and_b32_e32 v69, 0xffff0000, v128
	s_waitcnt lgkmcnt(2)
	v_mfma_f32_16x16x32_bf16 v[122:125], v[122:125], v[76:79], 0
	v_lshlrev_b32_e32 v74, 16, v129
	v_and_b32_e32 v75, 0xffff0000, v129
	ds_read_b128 v[126:129], v160 offset:13056
	s_waitcnt lgkmcnt(2)
	v_mfma_f32_16x16x32_bf16 v[122:125], v[130:133], v[80:83], v[122:125]
	v_sub_f32_e32 v145, v74, v72
	v_sub_f32_e32 v146, v75, v73
	ds_read2_b64 v[72:75], v108 offset0:8 offset1:12
	ds_read_b128 v[130:133], v160 offset:13120
	s_waitcnt lgkmcnt(3)
	v_mfma_f32_16x16x32_bf16 v[122:125], v[134:137], v[84:87], v[122:125]
	v_sub_f32_e32 v108, v68, v70
	ds_read_b128 v[134:137], v160 offset:13248
	v_pk_mul_f32 v[48:49], v[48:49], v[106:107] op_sel_hi:[1,0]
	v_mfma_f32_16x16x32_bf16 v[122:125], v[138:141], v[88:91], v[122:125]
	v_sub_f32_e32 v138, v69, v71
	ds_read_b128 v[68:71], v160 offset:13184
	s_waitcnt lgkmcnt(3)
	v_lshlrev_b32_e32 v139, 16, v72
	v_mfma_f32_16x16x32_bf16 v[126:129], v[126:129], v[76:79], 0
	v_and_b32_e32 v72, 0xffff0000, v72
	s_nop 1
	v_sub_f32_e32 v123, v72, v123
	v_lshlrev_b32_e32 v72, 16, v74
	s_waitcnt lgkmcnt(2)
	v_mfma_f32_16x16x32_bf16 v[126:129], v[130:133], v[80:83], v[126:129]
	v_lshlrev_b32_e32 v130, 16, v73
	v_and_b32_e32 v73, 0xffff0000, v73
	v_sub_f32_e32 v125, v73, v125
	s_waitcnt lgkmcnt(0)
	v_mfma_f32_16x16x32_bf16 v[68:71], v[68:71], v[84:87], v[126:129]
	v_and_b32_e32 v73, 0xffff0000, v74
	v_lshlrev_b32_e32 v74, 16, v75
	v_and_b32_e32 v75, 0xffff0000, v75
	v_mfma_f32_16x16x32_bf16 v[68:71], v[134:137], v[88:91], v[68:71]
	v_sub_f32_e32 v124, v130, v124
	v_sub_f32_e32 v122, v139, v122
	v_pk_mul_f32 v[46:47], v[46:47], v[106:107] op_sel_hi:[1,0]
	v_pk_mul_f32 v[44:45], v[44:45], v[106:107] op_sel_hi:[1,0]
	v_pk_mul_f32 v[42:43], v[42:43], v[106:107] op_sel_hi:[1,0]
	s_nop 2
	v_sub_f32_e32 v126, v74, v70
	v_sub_f32_e32 v71, v75, v71
	v_sub_f32_e32 v70, v72, v68
	v_sub_f32_e32 v127, v73, v69
	v_cvt_pk_bf16_f32 v72, v109, v144
	v_cvt_pk_bf16_f32 v73, v142, v143
	v_cvt_pk_bf16_f32 v74, v108, v138
	v_cvt_pk_bf16_f32 v75, v145, v146
	v_cvt_pk_bf16_f32 v68, v122, v123
	v_cvt_pk_bf16_f32 v69, v124, v125
	v_cvt_pk_bf16_f32 v70, v70, v127
	v_cvt_pk_bf16_f32 v71, v126, v71
	s_barrier
; #define PG8_LAS __attribute__((address_space(3)))
; __device__ __forceinline__ unsigned pk2c(float a, float b) { const f32x2_ v = {a, b}; const bf16x2_ r = __builtin_convertvector(v, bf16x2_); return __builtin_bit_cast(unsigned, r); }
; #define MFMA16(a, b, c) __builtin_amdgcn_mfma_f32_16x16x32_bf16((a), (b), (c), 0, 0, 0)
; __device__ __forceinline__ void phase_scan(const Args& a, PG8_LAS unsigned char* lds, int sblk) {
;     ...
;             for (int mt = 0; mt < 4; ++mt) {
;                 f32x4 o = {0.f, 0.f, 0.f, 0.f};
; #pragma unroll
;                 for (int s = 0; s < 4; ++s) { const bf16x8 af = *(const PG8_LAS bf16x8*)(lds + L_QG + (16 * mt + r) * 272 + (32 * s + 8 * q) * 2); o = MFMA16(af, Sb[s], o); }
; #pragma unroll
;                 for (int s = 0; s < 2; ++s) { const bf16x8 af = *(const PG8_LAS bf16x8*)(lds + L_AQ + (16 * mt + r) * 144 + (32 * s + 8 * q) * 2); o = MFMA16(af, Vb[s], o); }
; #pragma unroll
;                 for (int e = 0; e < 4; ++e) of[(row0 + 16 * mt + 4 * q + e) * 512 + h * 128 + dv0 + r] = (bf16_t)(pk2c(o[e], o[e]) & 0xffffu);
;             }
	ds_read_b128 v[122:125], v160 offset:17408
	ds_read_b128 v[126:129], v160 offset:17472
	s_waitcnt lgkmcnt(1)
	v_mfma_f32_16x16x32_bf16 v[122:125], v[122:125], v[76:79], 0
	ds_read_b128 v[130:133], v160 offset:17536
	v_lshlrev_b64 v[108:109], 10, v[94:95]
	v_lshl_add_u64 v[142:143], v[104:105], 0, v[108:109]
	s_waitcnt lgkmcnt(1)
	v_mfma_f32_16x16x32_bf16 v[122:125], v[126:129], v[80:83], v[122:125]
	ds_read_b128 v[126:129], v160 offset:17600
	v_pk_mul_f32 v[40:41], v[40:41], v[106:107] op_sel_hi:[1,0]
	v_pk_mul_f32 v[38:39], v[38:39], v[106:107] op_sel_hi:[1,0]
	s_waitcnt lgkmcnt(1)
	v_mfma_f32_16x16x32_bf16 v[122:125], v[130:133], v[84:87], v[122:125]
	ds_read_b128 v[130:133], v161
	v_pk_mul_f32 v[36:37], v[36:37], v[106:107] op_sel_hi:[1,0]
	v_pk_mul_f32 v[58:59], v[58:59], v[106:107] op_sel_hi:[1,0]
	s_waitcnt lgkmcnt(1)
	v_mfma_f32_16x16x32_bf16 v[122:125], v[126:129], v[88:91], v[122:125]
	ds_read_b128 v[126:129], v161 offset:64
	v_pk_mul_f32 v[56:57], v[56:57], v[106:107] op_sel_hi:[1,0]
	v_pk_mul_f32 v[62:63], v[62:63], v[106:107] op_sel_hi:[1,0]
	s_waitcnt lgkmcnt(1)
	v_mfma_f32_16x16x32_bf16 v[122:125], v[130:133], v[72:75], v[122:125]
	ds_read_b128 v[130:133], v160 offset:21760
	v_pk_mul_f32 v[60:61], v[60:61], v[106:107] op_sel_hi:[1,0]
	v_pk_mul_f32 v[66:67], v[66:67], v[106:107] op_sel_hi:[1,0]
	s_waitcnt lgkmcnt(1)
	v_mfma_f32_16x16x32_bf16 v[122:125], v[126:129], v[68:71], v[122:125]
	ds_read_b128 v[126:129], v160 offset:21824
	ds_read_b128 v[134:137], v160 offset:21888
	ds_read_b128 v[138:141], v160 offset:21952
	v_pk_mul_f32 v[64:65], v[64:65], v[106:107] op_sel_hi:[1,0]
	s_waitcnt lgkmcnt(3)
	v_mfma_f32_16x16x32_bf16 v[130:133], v[130:133], v[76:79], 0
	s_nop 1
	v_cvt_pk_bf16_f32 v122, v122, s0
	global_store_short v[142:143], v122, off
	v_cvt_pk_bf16_f32 v122, v123, s0
	s_waitcnt lgkmcnt(2)
	v_mfma_f32_16x16x32_bf16 v[126:129], v[126:129], v[80:83], v[130:133]
	global_store_short v[142:143], v122, off offset:1024
	v_cvt_pk_bf16_f32 v122, v124, s0
	global_store_short v[142:143], v122, off offset:2048
	ds_read_b128 v[130:133], v161 offset:2304
	s_waitcnt lgkmcnt(2)
	v_mfma_f32_16x16x32_bf16 v[126:129], v[134:137], v[84:87], v[126:129]
	ds_read_b128 v[134:137], v161 offset:2368
	v_cvt_pk_bf16_f32 v122, v125, s0
	global_store_short v[142:143], v122, off offset:3072
	s_waitcnt lgkmcnt(2)
	v_mfma_f32_16x16x32_bf16 v[126:129], v[138:141], v[88:91], v[126:129]
	v_mul_f32_e64 v54, v54, v106
	v_mul_f32_e64 v55, v55, v106
	v_pk_mul_f32 v[52:53], v[52:53], v[106:107] op_sel_hi:[1,0]
	s_waitcnt lgkmcnt(1)
	v_mfma_f32_16x16x32_bf16 v[126:129], v[130:133], v[72:75], v[126:129]
	v_or_b32_e32 v130, 0x4000, v108
	v_mov_b32_e32 v131, v109
	v_lshl_add_u64 v[130:131], v[104:105], 0, v[130:131]
	s_waitcnt lgkmcnt(0)
	v_mfma_f32_16x16x32_bf16 v[122:125], v[134:137], v[68:71], v[126:129]
	ds_read_b128 v[134:137], v160 offset:26240
	s_nop 1
	ds_read_b128 v[126:129], v160 offset:26112
	s_nop 3
	v_cvt_pk_bf16_f32 v122, v122, s0
	global_store_short v[130:131], v122, off
	ds_read_b128 v[130:133], v160 offset:26176
	s_waitcnt lgkmcnt(1)
	v_mfma_f32_16x16x32_bf16 v[126:129], v[126:129], v[76:79], 0
	v_cvt_pk_bf16_f32 v138, v123, s0
	v_or_b32_e32 v122, 0x4400, v108
	v_mov_b32_e32 v123, v109
	v_lshl_add_u64 v[122:123], v[104:105], 0, v[122:123]
	global_store_short v[122:123], v138, off
	ds_read_b128 v[138:141], v160 offset:26304
	s_waitcnt lgkmcnt(1)
	v_mfma_f32_16x16x32_bf16 v[126:129], v[130:133], v[80:83], v[126:129]
	ds_read_b128 v[130:133], v161 offset:4608
	v_or_b32_e32 v122, 0x4800, v108
	v_mov_b32_e32 v123, v109
	v_mfma_f32_16x16x32_bf16 v[126:129], v[134:137], v[84:87], v[126:129]
	ds_read_b128 v[134:137], v161 offset:4672
	v_cvt_pk_bf16_f32 v124, v124, s0
	v_lshl_add_u64 v[122:123], v[104:105], 0, v[122:123]
	s_waitcnt lgkmcnt(2)
	v_mfma_f32_16x16x32_bf16 v[126:129], v[138:141], v[88:91], v[126:129]
	global_store_short v[122:123], v124, off
	v_cvt_pk_bf16_f32 v140, v125, s0
	v_or_b32_e32 v138, 0x4c00, v108
	s_waitcnt lgkmcnt(1)
	v_mfma_f32_16x16x32_bf16 v[122:125], v[130:133], v[72:75], v[126:129]
	v_mov_b32_e32 v139, v109
	s_nop 1
	v_lshl_add_u64 v[126:127], v[104:105], 0, v[138:139]
	global_store_short v[126:127], v140, off
	s_waitcnt lgkmcnt(0)
	v_mfma_f32_16x16x32_bf16 v[122:125], v[134:137], v[68:71], v[122:125]
	v_or_b32_e32 v126, 0x8000, v108
	v_mov_b32_e32 v127, v109
	v_lshl_add_u64 v[130:131], v[104:105], 0, v[126:127]
	ds_read_b128 v[126:129], v160 offset:30464
	s_nop 3
	v_cvt_pk_bf16_f32 v122, v122, s0
	global_store_short v[130:131], v122, off
	ds_read_b128 v[130:133], v160 offset:30528
	v_cvt_pk_bf16_f32 v134, v123, s0
	v_or_b32_e32 v122, 0x8400, v108
	v_mov_b32_e32 v123, v109
	v_lshl_add_u64 v[122:123], v[104:105], 0, v[122:123]
	global_store_short v[122:123], v134, off
	ds_read_b128 v[134:137], v160 offset:30592
	s_waitcnt lgkmcnt(2)
	v_mfma_f32_16x16x32_bf16 v[76:79], v[126:129], v[76:79], 0
	ds_read_b128 v[126:129], v160 offset:30656
	v_or_b32_e32 v122, 0x8800, v108
	v_mov_b32_e32 v123, v109
	s_waitcnt lgkmcnt(2)
	v_mfma_f32_16x16x32_bf16 v[76:79], v[130:133], v[80:83], v[76:79]
	ds_read_b128 v[80:83], v161 offset:6912
	v_cvt_pk_bf16_f32 v124, v124, s0
	v_lshl_add_u64 v[122:123], v[104:105], 0, v[122:123]
	s_waitcnt lgkmcnt(2)
	v_mfma_f32_16x16x32_bf16 v[76:79], v[134:137], v[84:87], v[76:79]
	ds_read_b128 v[84:87], v161 offset:6976
	global_store_short v[122:123], v124, off
	v_add3_u32 v124, v107, v112, s65
	s_waitcnt lgkmcnt(2)
	v_mfma_f32_16x16x32_bf16 v[76:79], v[126:129], v[88:91], v[76:79]
	v_or_b32_e32 v88, 0x8c00, v108
	v_mov_b32_e32 v89, v109
	v_cvt_pk_bf16_f32 v122, v125, s0
	s_waitcnt lgkmcnt(1)
	v_mfma_f32_16x16x32_bf16 v[76:79], v[80:83], v[72:75], v[76:79]
	v_lshl_add_u64 v[88:89], v[104:105], 0, v[88:89]
	global_store_short v[88:89], v122, off
	s_waitcnt lgkmcnt(0)
	v_mfma_f32_16x16x32_bf16 v[76:79], v[84:87], v[68:71], v[76:79]
	s_barrier
; #define PG8_LAS __attribute__((address_space(3)))
; #define MFMA16(a, b, c) __builtin_amdgcn_mfma_f32_16x16x32_bf16((a), (b), (c), 0, 0, 0)
; __device__ __forceinline__ void phase_scan(const Args& a, PG8_LAS unsigned char* lds, int sblk) {
;     ...
; #pragma unroll
;             for (int mt = 0; mt < 8; ++mt) {
;                 f32x4 acc = S[mt] * gl;
; #pragma unroll
;                 for (int s = 0; s < 2; ++s) { const bf16x8 af = *(const PG8_LAS bf16x8*)(lds + L_KD + (16 * mt + r) * 144 + (32 * s + 8 * q) * 2); acc = MFMA16(af, Vb[s], acc); }
;                 S[mt] = acc;
;             }
;             __builtin_amdgcn_s_setprio(0);
;         }
;         __syncthreads();
;     }
	ds_read_b128 v[80:83], v124 offset:34816
	ds_read_b128 v[84:87], v124 offset:34880
	ds_read_b128 v[88:91], v124 offset:37120
	v_or_b32_e32 v122, 0xc000, v108
	s_waitcnt lgkmcnt(2)
	v_mfma_f32_16x16x32_bf16 v[48:51], v[80:83], v[72:75], v[48:51]
	ds_read_b128 v[80:83], v124 offset:37184
	v_mov_b32_e32 v123, v109
	s_nop 0
	v_cvt_pk_bf16_f32 v76, v76, s0
	s_waitcnt lgkmcnt(2)
	v_mfma_f32_16x16x32_bf16 v[48:51], v[84:87], v[68:71], v[48:51]
	ds_read_b128 v[84:87], v124 offset:39424
	v_cvt_pk_bf16_f32 v78, v78, s0
	s_waitcnt lgkmcnt(2)
	v_mfma_f32_16x16x32_bf16 v[44:47], v[88:91], v[72:75], v[44:47]
	v_lshl_add_u64 v[88:89], v[104:105], 0, v[122:123]
	global_store_short v[88:89], v76, off
	ds_read_b128 v[88:91], v124 offset:39488
	s_waitcnt lgkmcnt(2)
	v_mfma_f32_16x16x32_bf16 v[44:47], v[80:83], v[68:71], v[44:47]
	ds_read_b128 v[80:83], v124 offset:41728
	v_cvt_pk_bf16_f32 v122, v77, s0
	v_or_b32_e32 v76, 0xc400, v108
	s_waitcnt lgkmcnt(2)
	v_mfma_f32_16x16x32_bf16 v[40:43], v[84:87], v[72:75], v[40:43]
	ds_read_b128 v[84:87], v124 offset:41792
	v_mov_b32_e32 v77, v109
	v_lshl_add_u64 v[76:77], v[104:105], 0, v[76:77]
	s_waitcnt lgkmcnt(2)
	v_mfma_f32_16x16x32_bf16 v[40:43], v[88:91], v[68:71], v[40:43]
	ds_read_b128 v[88:91], v124 offset:44032
	global_store_short v[76:77], v122, off
	v_or_b32_e32 v76, 0xc800, v108
	s_waitcnt lgkmcnt(2)
	v_mfma_f32_16x16x32_bf16 v[36:39], v[80:83], v[72:75], v[36:39]
	ds_read_b128 v[80:83], v124 offset:44096
	v_mov_b32_e32 v77, v109
	v_lshl_add_u64 v[76:77], v[104:105], 0, v[76:77]
	s_waitcnt lgkmcnt(2)
	v_mfma_f32_16x16x32_bf16 v[36:39], v[84:87], v[68:71], v[36:39]
	ds_read_b128 v[84:87], v124 offset:46336
	v_or_b32_e32 v108, 0xcc00, v108
	global_store_short v[76:77], v78, off
	s_waitcnt lgkmcnt(2)
	v_mfma_f32_16x16x32_bf16 v[56:59], v[88:91], v[72:75], v[56:59]
	ds_read_b128 v[88:91], v124 offset:46400
	v_cvt_pk_bf16_f32 v76, v79, s0
	s_waitcnt lgkmcnt(2)
	v_mfma_f32_16x16x32_bf16 v[56:59], v[80:83], v[68:71], v[56:59]
	ds_read_b128 v[80:83], v124 offset:48640
	s_waitcnt lgkmcnt(2)
	v_mfma_f32_16x16x32_bf16 v[60:63], v[84:87], v[72:75], v[60:63]
	ds_read_b128 v[84:87], v124 offset:48704
	s_waitcnt lgkmcnt(2)
	v_mfma_f32_16x16x32_bf16 v[60:63], v[88:91], v[68:71], v[60:63]
	ds_read_b128 v[88:91], v124 offset:50944
	s_waitcnt lgkmcnt(2)
	v_mfma_f32_16x16x32_bf16 v[64:67], v[80:83], v[72:75], v[64:67]
	ds_read_b128 v[80:83], v124 offset:51008
	s_waitcnt lgkmcnt(1)
	v_mfma_f32_16x16x32_bf16 v[52:55], v[88:91], v[72:75], v[52:55]
	v_lshl_add_u64 v[72:73], v[104:105], 0, v[108:109]
	global_store_short v[72:73], v76, off
	v_mfma_f32_16x16x32_bf16 v[64:67], v[84:87], v[68:71], v[64:67]
	s_waitcnt lgkmcnt(0)
	v_mfma_f32_16x16x32_bf16 v[52:55], v[80:83], v[68:71], v[52:55]
	s_setprio 0
	s_sub_i32 s64, 80896, s64
	s_sub_i32 s65, 96512, s65
	s_sub_i32 s66, 78080, s66
	s_sub_i32 s67, s68, s67
	v_add_u32_e32 v94, 64, v94
	s_waitcnt lgkmcnt(0)
	s_barrier
	s_add_i32 s57, s57, 1
	s_cmp_lt_u32 s57, 32
	s_cbranch_scc1 .Lsc_cs_loop
